# seam code-prefetch windows sized to the next phase's code (2-4 loads) instead of a fixed 32 KB
# speedup vs baseline: 1.0016x; 1.0016x over previous
.Lxb_pf_5:
	v_readlane_b32 s18, v252, 5
	s_nop 3
	s_and_b32 s18, s18, 56
	s_cmp_lg_u32 s18, 0
	s_cbranch_scc1 .Lxb_wait_5
	s_getpc_b64 s[18:19]
	s_mov_b64 s[22:23], exec
	s_mov_b64 exec, -1
	v_mbcnt_lo_u32_b32 v254, -1, 0
	v_mbcnt_hi_u32_b32 v254, -1, v254
	v_lshlrev_b32_e32 v254, 7, v254
	global_load_dword v255, v254, s[18:19]
	s_add_u32 s18, s18, 0x2000
	s_addc_u32 s19, s19, 0
	global_load_dword v255, v254, s[18:19]
	s_mov_b64 exec, s[22:23]
